# v41 plus NA next-group K-fragment ds_reads issued before the current group's QK MFMAs (renamed fragment registers, counted lgkmcnt)
# baseline (speedup 1.0000x reference)
; #define LAS __attribute__((address_space(3)))
; #define MFMA32(a, b, c) __builtin_amdgcn_mfma_f32_16x16x32_bf16((a), (b), (c), 0, 0, 0)
; DI void na_phase(LAS unsigned char* lds, const Args& A, const bf16* proj, bf16* nao, int T, int nB, unsigned* counter, int tid_in) {
;     ...
;             for (int rr = 0; rr < 4; ++rr) { const int kr = rs + 4 * kh + rr, sl = kr & 7;
; #pragma unroll
;                 for (int ct = 0; ct < 2; ++ct) { const int cm = cs0 + 16 * ct + l15; f32x4 acc = (f32x4){0.f, 0.f, 0.f, 0.f};
; #pragma unroll
;                     for (int ks = 0; ks < 2; ++ks) { const bf16x8 kf = *(const LAS bf16x8*)(lds + NA_K + sl * 8192 + cm * 128 + (((4 * ks + g) ^ ((cm >> 1) & 7)) * 16)); acc = MFMA32(kf, qf[ks], acc); }
; #pragma unroll
;                     for (int e = 0; e < 4; ++e) { const int cc = cs0 + 16 * ct + 4 * g + e; const bool valid = (cc >= csq) && (cc < csq + 16);
;                         const int bi = (kr - r + 7) * 31 + min(max(cc - cq + 15, 0), 30);
;                         const float sv = valid ? acc[e] + BI[bi] : -INFINITY; acc[e] = sv; mx = fmaxf(mx, sv); }
;                     sT[rr][ct] = acc; } }
.LBB0_337:
	v_add_u32_e32 v31, s38, v71
	v_lshlrev_b32_e32 v24, 13, v31
	v_and_b32_e32 v28, 0xe000, v24
	v_add_u32_e32 v30, 0, v28
	v_add_u32_e32 v29, v30, v91
	v_add_u32_e32 v24, v29, v92
	ds_read_b128 v[24:27], v24
	v_add_u32_e32 v29, v29, v93
	ds_read_b128 v[58:61], v29
	s_add_i32 s0, s19, s38
	v_add_u32_e32 v29, s0, v57
	v_mul_lo_u32 v29, v29, s88
	v_add_u32_e32 v38, s87, v29
	v_add_u32_e32 v29, 0xfffff080, v38
	v_mov_b32_e32 v63, 0xff800000
	v_lshl_add_u32 v252, v94, 2, v29
	ds_read_b32 v252, v252 offset:868
	v_lshl_add_u32 v253, v95, 2, v29
	ds_read_b32 v253, v253 offset:868
	v_lshl_add_u32 v254, v96, 2, v29
	ds_read_b32 v254, v254 offset:868
	v_lshl_add_u32 v255, v97, 2, v29
	ds_read_b32 v255, v255 offset:868
	v_add_u32_e32 v30, v30, v98
	v_add_u32_e32 v156, v30, v92
	ds_read_b128 v[140:143], v156
	v_add_u32_e32 v30, v30, v93
	ds_read_b128 v[144:147], v30
	s_waitcnt lgkmcnt(7)
	v_mfma_f32_16x16x32_bf16 v[24:27], v[24:27], v[20:23], 0
	s_waitcnt lgkmcnt(6)
	v_mfma_f32_16x16x32_bf16 v[24:27], v[58:61], v[16:19], v[24:27]
	v_mov_b32_e32 v59, 0xff800000
	s_waitcnt lgkmcnt(2)
	s_nop 5
	s_and_saveexec_b64 s[0:1], s[14:15]
	v_add_f32_e32 v63, v24, v252
	s_or_b64 exec, exec, s[0:1]
	s_and_saveexec_b64 s[0:1], s[16:17]
	v_add_f32_e32 v59, v25, v253
	s_or_b64 exec, exec, s[0:1]
	v_mov_b32_e32 v56, 0xff800000
	v_mov_b32_e32 v62, 0xff800000
	s_and_saveexec_b64 s[0:1], s[48:49]
	v_add_f32_e32 v62, v26, v254
	s_or_b64 exec, exec, s[0:1]
	s_and_saveexec_b64 s[0:1], s[50:51]
	v_add_f32_e32 v56, v27, v255
	s_or_b64 exec, exec, s[0:1]
	v_mov_b32_e32 v39, 0xff800000
	v_lshl_add_u32 v252, v99, 2, v29
	ds_read_b32 v252, v252 offset:868
	v_lshl_add_u32 v253, v100, 2, v29
	ds_read_b32 v253, v253 offset:868
	v_lshl_add_u32 v254, v101, 2, v29
	ds_read_b32 v254, v254 offset:868
	v_lshl_add_u32 v255, v102, 2, v29
	ds_read_b32 v255, v255 offset:868
	v_lshl_add_u32 v156, v31, 13, v212
	v_and_b32_e32 v29, 0xe000, v156
	v_add_u32_e32 v66, 0, v29
	v_add_u32_e32 v30, v66, v91
	v_add_u32_e32 v156, v30, v92
	ds_read_b128 v[148:151], v156
	v_add_u32_e32 v30, v30, v93
	ds_read_b128 v[152:155], v30
	s_waitcnt lgkmcnt(7)
	v_mfma_f32_16x16x32_bf16 v[24:27], v[140:143], v[20:23], 0
	s_waitcnt lgkmcnt(6)
	v_mfma_f32_16x16x32_bf16 v[24:27], v[144:147], v[16:19], v[24:27]
	v_mov_b32_e32 v65, 0xff800000
	s_waitcnt lgkmcnt(2)
	s_nop 5
	s_and_saveexec_b64 s[0:1], s[52:53]
	v_add_f32_e32 v65, v24, v252
	s_or_b64 exec, exec, s[0:1]
	s_and_saveexec_b64 s[0:1], s[56:57]
	v_add_f32_e32 v39, v25, v253
	s_or_b64 exec, exec, s[0:1]
	v_mov_b32_e32 v54, 0xff800000
	v_mov_b32_e32 v55, 0xff800000
	s_and_saveexec_b64 s[0:1], s[76:77]
	v_add_f32_e32 v55, v26, v254
	s_or_b64 exec, exec, s[0:1]
	s_and_saveexec_b64 s[0:1], s[66:67]
	v_add_f32_e32 v54, v27, v255
	s_or_b64 exec, exec, s[0:1]
	v_add_u32_e32 v30, 0xfffff0fc, v38
	v_mov_b32_e32 v58, 0xff800000
	v_mov_b32_e32 v60, 0xff800000
	v_lshl_add_u32 v252, v94, 2, v30
	ds_read_b32 v252, v252 offset:868
	v_lshl_add_u32 v253, v95, 2, v30
	ds_read_b32 v253, v253 offset:868
	v_lshl_add_u32 v254, v96, 2, v30
	ds_read_b32 v254, v254 offset:868
	v_lshl_add_u32 v255, v97, 2, v30
	ds_read_b32 v255, v255 offset:868
	v_add_u32_e32 v66, v66, v98
	v_add_u32_e32 v156, v66, v92
	ds_read_b128 v[140:143], v156
	v_add_u32_e32 v66, v66, v93
	ds_read_b128 v[144:147], v66
	s_waitcnt lgkmcnt(7)
	v_mfma_f32_16x16x32_bf16 v[24:27], v[148:151], v[20:23], 0
	s_waitcnt lgkmcnt(6)
	v_mfma_f32_16x16x32_bf16 v[24:27], v[152:155], v[16:19], v[24:27]
	s_waitcnt lgkmcnt(2)
	s_nop 5
	s_and_saveexec_b64 s[0:1], s[14:15]
	v_add_f32_e32 v60, v24, v252
	s_or_b64 exec, exec, s[0:1]
	s_and_saveexec_b64 s[0:1], s[16:17]
	v_add_f32_e32 v58, v25, v253
	s_or_b64 exec, exec, s[0:1]
	v_mov_b32_e32 v61, 0xff800000
	v_mov_b32_e32 v64, 0xff800000
	s_and_saveexec_b64 s[0:1], s[48:49]
	v_add_f32_e32 v64, v26, v254
	s_or_b64 exec, exec, s[0:1]
	s_and_saveexec_b64 s[0:1], s[50:51]
	v_add_f32_e32 v61, v27, v255
	s_or_b64 exec, exec, s[0:1]
	v_mov_b32_e32 v66, 0xff800000
	v_mov_b32_e32 v67, 0xff800000
	v_lshl_add_u32 v252, v99, 2, v30
	ds_read_b32 v252, v252 offset:868
	v_lshl_add_u32 v253, v100, 2, v30
	ds_read_b32 v253, v253 offset:868
	v_lshl_add_u32 v254, v101, 2, v30
	ds_read_b32 v254, v254 offset:868
	v_lshl_add_u32 v255, v102, 2, v30
	ds_read_b32 v255, v255 offset:868
	v_lshl_add_u32 v156, v31, 13, v213
	v_and_b32_e32 v30, 0xe000, v156
	v_add_u32_e32 v110, 0, v30
	v_add_u32_e32 v106, v110, v91
	v_add_u32_e32 v156, v106, v92
	ds_read_b128 v[148:151], v156
	v_add_u32_e32 v106, v106, v93
	ds_read_b128 v[152:155], v106
	s_waitcnt lgkmcnt(7)
	v_mfma_f32_16x16x32_bf16 v[24:27], v[140:143], v[20:23], 0
	s_waitcnt lgkmcnt(6)
	v_mfma_f32_16x16x32_bf16 v[24:27], v[144:147], v[16:19], v[24:27]
	s_waitcnt lgkmcnt(2)
	s_nop 5
	s_and_saveexec_b64 s[0:1], s[52:53]
	v_add_f32_e32 v67, v24, v252
	s_or_b64 exec, exec, s[0:1]
	s_and_saveexec_b64 s[0:1], s[56:57]
	v_add_f32_e32 v66, v25, v253
	s_or_b64 exec, exec, s[0:1]
	v_mov_b32_e32 v104, 0xff800000
	v_mov_b32_e32 v105, 0xff800000
	s_and_saveexec_b64 s[0:1], s[76:77]
	v_add_f32_e32 v105, v26, v254
	s_or_b64 exec, exec, s[0:1]
	s_and_saveexec_b64 s[0:1], s[66:67]
	v_add_f32_e32 v104, v27, v255
	s_or_b64 exec, exec, s[0:1]
	v_add_u32_e32 v114, 0xfffff178, v38
	v_lshl_add_u32 v252, v94, 2, v114
	ds_read_b32 v252, v252 offset:868
	v_lshl_add_u32 v253, v95, 2, v114
	ds_read_b32 v253, v253 offset:868
	v_lshl_add_u32 v254, v96, 2, v114
	ds_read_b32 v254, v254 offset:868
	v_lshl_add_u32 v255, v97, 2, v114
	ds_read_b32 v255, v255 offset:868
	v_add_u32_e32 v110, v110, v98
	v_add_u32_e32 v156, v110, v92
	ds_read_b128 v[140:143], v156
	v_add_u32_e32 v110, v110, v93
	ds_read_b128 v[144:147], v110
	s_waitcnt lgkmcnt(7)
; #define LAS __attribute__((address_space(3)))
; #define MFMA32(a, b, c) __builtin_amdgcn_mfma_f32_16x16x32_bf16((a), (b), (c), 0, 0, 0)
; DI void na_phase(LAS unsigned char* lds, const Args& A, const bf16* proj, bf16* nao, int T, int nB, unsigned* counter, int tid_in) {
;     ...
;             for (int rr = 0; rr < 4; ++rr) { const int kr = rs + 4 * kh + rr, sl = kr & 7;
; #pragma unroll
;                 for (int ct = 0; ct < 2; ++ct) { const int cm = cs0 + 16 * ct + l15; f32x4 acc = (f32x4){0.f, 0.f, 0.f, 0.f};
; #pragma unroll
;                     for (int ks = 0; ks < 2; ++ks) { const bf16x8 kf = *(const LAS bf16x8*)(lds + NA_K + sl * 8192 + cm * 128 + (((4 * ks + g) ^ ((cm >> 1) & 7)) * 16)); acc = MFMA32(kf, qf[ks], acc); }
; #pragma unroll
;                     for (int e = 0; e < 4; ++e) { const int cc = cs0 + 16 * ct + 4 * g + e; const bool valid = (cc >= csq) && (cc < csq + 16);
;                         const int bi = (kr - r + 7) * 31 + min(max(cc - cq + 15, 0), 30);
;                         const float sv = valid ? acc[e] + BI[bi] : -INFINITY; acc[e] = sv; mx = fmaxf(mx, sv); }
;                     sT[rr][ct] = acc; } }
;             mx = fmaxf(mx, __shfl_xor(mx, 16)); mx = fmaxf(mx, __shfl_xor(mx, 32));
;             float lsum = 0.f;
; #pragma unroll
;             for (int rr = 0; rr < 4; ++rr)
; #pragma unroll
;                 for (int ct = 0; ct < 2; ++ct)
; #pragma unroll
;                     for (int e = 0; e < 4; ++e) { const float p = __expf(sT[rr][ct][e] - mx); sT[rr][ct][e] = p; lsum += p; }
	v_mfma_f32_16x16x32_bf16 v[24:27], v[148:151], v[20:23], 0
	s_waitcnt lgkmcnt(6)
	v_mfma_f32_16x16x32_bf16 v[24:27], v[152:155], v[16:19], v[24:27]
	v_mov_b32_e32 v106, 0xff800000
	v_mov_b32_e32 v107, 0xff800000
	s_waitcnt lgkmcnt(2)
	s_nop 5
	s_and_saveexec_b64 s[0:1], s[14:15]
	v_add_f32_e32 v107, v24, v252
	s_or_b64 exec, exec, s[0:1]
	s_and_saveexec_b64 s[0:1], s[16:17]
	v_add_f32_e32 v106, v25, v253
	s_or_b64 exec, exec, s[0:1]
	v_mov_b32_e32 v108, 0xff800000
	v_mov_b32_e32 v109, 0xff800000
	s_and_saveexec_b64 s[0:1], s[48:49]
	v_add_f32_e32 v109, v26, v254
	s_or_b64 exec, exec, s[0:1]
	s_and_saveexec_b64 s[0:1], s[50:51]
	v_add_f32_e32 v108, v27, v255
	s_or_b64 exec, exec, s[0:1]
	v_lshl_add_u32 v252, v99, 2, v114
	ds_read_b32 v252, v252 offset:868
	v_lshl_add_u32 v253, v100, 2, v114
	ds_read_b32 v253, v253 offset:868
	v_lshl_add_u32 v254, v101, 2, v114
	ds_read_b32 v254, v254 offset:868
	v_lshl_add_u32 v255, v102, 2, v114
	ds_read_b32 v255, v255 offset:868
	v_lshl_add_u32 v156, v31, 13, v214
	v_and_b32_e32 v31, 0xe000, v156
	v_add_u32_e32 v116, 0, v31
	v_add_u32_e32 v114, v116, v91
	v_add_u32_e32 v156, v114, v92
	ds_read_b128 v[148:151], v156
	v_add_u32_e32 v114, v114, v93
	ds_read_b128 v[152:155], v114
	s_waitcnt lgkmcnt(7)
	v_mfma_f32_16x16x32_bf16 v[24:27], v[140:143], v[20:23], 0
	s_waitcnt lgkmcnt(6)
	v_mfma_f32_16x16x32_bf16 v[24:27], v[144:147], v[16:19], v[24:27]
	v_mov_b32_e32 v110, 0xff800000
	v_mov_b32_e32 v111, 0xff800000
	s_waitcnt lgkmcnt(2)
	s_nop 5
	s_and_saveexec_b64 s[0:1], s[52:53]
	v_add_f32_e32 v111, v24, v252
	s_or_b64 exec, exec, s[0:1]
	s_and_saveexec_b64 s[0:1], s[56:57]
	v_add_f32_e32 v110, v25, v253
	s_or_b64 exec, exec, s[0:1]
	v_mov_b32_e32 v112, 0xff800000
	v_mov_b32_e32 v113, 0xff800000
	s_and_saveexec_b64 s[0:1], s[76:77]
	v_add_f32_e32 v113, v26, v254
	s_or_b64 exec, exec, s[0:1]
	s_and_saveexec_b64 s[0:1], s[66:67]
	v_add_f32_e32 v112, v27, v255
	s_or_b64 exec, exec, s[0:1]
	v_add_u32_e32 v38, 0xfffff1f4, v38
	v_mov_b32_e32 v114, 0xff800000
	v_mov_b32_e32 v115, 0xff800000
	v_lshl_add_u32 v252, v94, 2, v38
	ds_read_b32 v252, v252 offset:868
	v_lshl_add_u32 v253, v95, 2, v38
	ds_read_b32 v253, v253 offset:868
	s_waitcnt lgkmcnt(3)
	v_mfma_f32_16x16x32_bf16 v[24:27], v[148:151], v[20:23], 0
	s_waitcnt lgkmcnt(2)
	v_mfma_f32_16x16x32_bf16 v[24:27], v[152:155], v[16:19], v[24:27]
	s_waitcnt lgkmcnt(0)
	s_nop 5
	s_and_saveexec_b64 s[0:1], s[14:15]
	v_add_f32_e32 v115, v24, v252
	s_or_b64 exec, exec, s[0:1]
	s_and_saveexec_b64 s[0:1], s[16:17]
	v_add_f32_e32 v114, v25, v253
	s_or_b64 exec, exec, s[0:1]
	s_nop 1
	v_mov_b32_e32 v24, 0xff800000
	v_mov_b32_e32 v25, 0xff800000
	v_lshl_add_u32 v252, v96, 2, v38
	ds_read_b32 v252, v252 offset:868
	v_lshl_add_u32 v253, v97, 2, v38
	ds_read_b32 v253, v253 offset:868
	s_waitcnt lgkmcnt(0)
	s_nop 2
	s_and_saveexec_b64 s[0:1], s[48:49]
	v_add_f32_e32 v25, v26, v252
	s_or_b64 exec, exec, s[0:1]
	s_and_saveexec_b64 s[0:1], s[50:51]
	v_add_f32_e32 v24, v27, v253
	s_or_b64 exec, exec, s[0:1]
	v_add_u32_e32 v26, v116, v98
	v_add_u32_e32 v27, v26, v92
	ds_read_b128 v[116:119], v27
	v_add_u32_e32 v26, v26, v93
	s_waitcnt lgkmcnt(0)
	v_mfma_f32_16x16x32_bf16 v[20:23], v[116:119], v[20:23], 0
	ds_read_b128 v[116:119], v26
	s_waitcnt lgkmcnt(0)
	v_mfma_f32_16x16x32_bf16 v[16:19], v[116:119], v[16:19], v[20:23]
	s_nop 4
	v_mov_b32_e32 v20, 0xff800000
	v_mov_b32_e32 v21, 0xff800000
	v_lshl_add_u32 v252, v99, 2, v38
	ds_read_b32 v252, v252 offset:868
	v_lshl_add_u32 v253, v100, 2, v38
	ds_read_b32 v253, v253 offset:868
	v_lshl_add_u32 v254, v101, 2, v38
	ds_read_b32 v254, v254 offset:868
	v_lshl_add_u32 v255, v102, 2, v38
	ds_read_b32 v255, v255 offset:868
	s_waitcnt lgkmcnt(0)
	s_and_saveexec_b64 s[0:1], s[52:53]
	v_add_f32_e32 v21, v16, v252
	s_or_b64 exec, exec, s[0:1]
	s_and_saveexec_b64 s[0:1], s[56:57]
	v_add_f32_e32 v20, v17, v253
	s_or_b64 exec, exec, s[0:1]
	v_mov_b32_e32 v16, 0xff800000
	v_mov_b32_e32 v17, 0xff800000
	s_and_saveexec_b64 s[0:1], s[76:77]
	v_add_f32_e32 v17, v18, v254
	s_or_b64 exec, exec, s[0:1]
	s_and_saveexec_b64 s[0:1], s[66:67]
	v_add_f32_e32 v16, v19, v255
	s_or_b64 exec, exec, s[0:1]
	v_max3_f32 v18, v63, s89, v59
	v_max3_f32 v18, v18, v62, v56
	v_max3_f32 v18, v18, v65, v39
	v_max3_f32 v18, v18, v55, v54
	v_max3_f32 v18, v18, v60, v58
	v_max3_f32 v18, v18, v64, v61
	v_max3_f32 v18, v18, v67, v66
	v_max3_f32 v18, v18, v105, v104
	v_max3_f32 v18, v18, v107, v106
	v_max3_f32 v18, v18, v109, v108
	v_max3_f32 v18, v18, v111, v110
	v_max3_f32 v18, v18, v113, v112
	v_max3_f32 v18, v18, v115, v114
	v_max3_f32 v18, v18, v25, v24
	v_max3_f32 v18, v18, v21, v20
	v_max3_f32 v18, v18, v17, v16
	v_mov_b32_e32 v19, v18
	s_nop 1
	v_permlane16_swap_b32_e32 v19, v18
	v_max_f32_e32 v18, v18, v19
	v_mov_b32_e32 v19, v18
	s_nop 1
	v_permlane32_swap_b32_e32 v19, v18
	v_max_f32_e32 v38, v18, v19
	v_sub_f32_e32 v39, v39, v38
	v_mul_f32_e32 v39, 0x3fb8aa3b, v39
	v_sub_f32_e32 v26, v56, v38
	v_exp_f32_e32 v56, v39
	v_sub_f32_e32 v39, v55, v38
	v_mul_f32_e32 v39, 0x3fb8aa3b, v39
	v_exp_f32_e32 v55, v39
	v_sub_f32_e32 v39, v54, v38
	v_mul_f32_e32 v39, 0x3fb8aa3b, v39
	v_sub_f32_e32 v22, v59, v38
	v_exp_f32_e32 v59, v39
	v_sub_f32_e32 v39, v60, v38
	v_mul_f32_e32 v39, 0x3fb8aa3b, v39
	v_exp_f32_e32 v116, v39
	v_sub_f32_e32 v39, v58, v38
	v_mul_f32_e32 v39, 0x3fb8aa3b, v39
	v_exp_f32_e32 v117, v39
	v_sub_f32_e32 v39, v64, v38
	v_mul_f32_e32 v39, 0x3fb8aa3b, v39
	v_exp_f32_e32 v118, v39
	v_sub_f32_e32 v39, v61, v38
	v_mul_f32_e32 v39, 0x3fb8aa3b, v39
	v_exp_f32_e32 v119, v39
	v_sub_f32_e32 v39, v67, v38
	v_sub_f32_e32 v18, v63, v38
	v_mul_f32_e32 v39, 0x3fb8aa3b, v39
; #define LAS __attribute__((address_space(3)))
; DI unsigned pk2(float lo, float hi) { f32x2 v = {lo, hi}; bf16v2 b = __builtin_convertvector(v, bf16v2); return __builtin_bit_cast(unsigned, b); }
; #define MFMA32(a, b, c) __builtin_amdgcn_mfma_f32_16x16x32_bf16((a), (b), (c), 0, 0, 0)
; DI void na_phase(LAS unsigned char* lds, const Args& A, const bf16* proj, bf16* nao, int T, int nB, unsigned* counter, int tid_in) {
;     ...
;             float lsum = 0.f;
; #pragma unroll
;             for (int rr = 0; rr < 4; ++rr)
; #pragma unroll
;                 for (int ct = 0; ct < 2; ++ct)
; #pragma unroll
;                     for (int e = 0; e < 4; ++e) { const float p = __expf(sT[rr][ct][e] - mx); sT[rr][ct][e] = p; lsum += p; }
;             lsum += __shfl_xor(lsum, 16); lsum += __shfl_xor(lsum, 32);
;             f32x4 O[4];
; #pragma unroll
;             for (int mt = 0; mt < 4; ++mt) O[mt] = (f32x4){0.f, 0.f, 0.f, 0.f};
; #pragma unroll
;             for (int rr = 0; rr < 4; ++rr) { const int sl = (rs + 4 * kh + rr) & 7;
;                 const u32x4 pw = (u32x4){pk2(sT[rr][0][0], sT[rr][0][1]), pk2(sT[rr][0][2], sT[rr][0][3]), pk2(sT[rr][1][0], sT[rr][1][1]), pk2(sT[rr][1][2], sT[rr][1][3])};
;                 const bf16x8 pb = __builtin_bit_cast(bf16x8, pw);
; #pragma unroll
;                 for (int mt = 0; mt < 4; ++mt) { const int dd = 16 * mt + l15, sw = 2 * ((dd >> 1) & 7);
;                     const LAS unsigned char* vb = lds + NA_V + sl * 8192 + dd * 128;
;                     const u32x2 lo = *(const LAS u32x2*)(vb + ((((cs0 >> 2) + g) ^ sw) * 8)), hi = *(const LAS u32x2*)(vb + ((((cs0 >> 2) + 4 + g) ^ sw) * 8));
;                     const u32x4 vv = (u32x4){lo.x, lo.y, hi.x, hi.y};
;                     O[mt] = MFMA32(__builtin_bit_cast(bf16x8, vv), pb, O[mt]); } }
	v_mul_f32_e32 v18, 0x3fb8aa3b, v18
	v_exp_f32_e32 v67, v39
	v_sub_f32_e32 v39, v66, v38
	v_exp_f32_e32 v18, v18
	v_mul_f32_e32 v22, 0x3fb8aa3b, v22
	v_sub_f32_e32 v23, v62, v38
	v_mul_f32_e32 v39, 0x3fb8aa3b, v39
	v_exp_f32_e32 v22, v22
	v_mul_f32_e32 v23, 0x3fb8aa3b, v23
	v_exp_f32_e32 v66, v39
	v_sub_f32_e32 v39, v105, v38
	v_exp_f32_e32 v23, v23
	v_mul_f32_e32 v26, 0x3fb8aa3b, v26
	v_sub_f32_e32 v27, v65, v38
	v_mul_f32_e32 v39, 0x3fb8aa3b, v39
	v_exp_f32_e32 v26, v26
	v_mul_f32_e32 v27, 0x3fb8aa3b, v27
	v_exp_f32_e32 v120, v39
	v_sub_f32_e32 v39, v104, v38
	v_add_f32_e32 v19, 0, v18
	v_exp_f32_e32 v27, v27
	v_mul_f32_e32 v39, 0x3fb8aa3b, v39
	v_add_f32_e32 v19, v22, v19
	v_exp_f32_e32 v121, v39
	v_sub_f32_e32 v39, v107, v38
	v_add_f32_e32 v19, v23, v19
	v_mul_f32_e32 v39, 0x3fb8aa3b, v39
	v_add_f32_e32 v19, v26, v19
	v_exp_f32_e32 v122, v39
	v_sub_f32_e32 v39, v106, v38
	v_add_f32_e32 v19, v27, v19
	v_mul_f32_e32 v39, 0x3fb8aa3b, v39
	v_add_f32_e32 v19, v56, v19
	v_exp_f32_e32 v123, v39
	v_sub_f32_e32 v39, v109, v38
	v_add_f32_e32 v19, v55, v19
	v_mul_f32_e32 v39, 0x3fb8aa3b, v39
	v_add_f32_e32 v19, v59, v19
	v_exp_f32_e32 v124, v39
	v_sub_f32_e32 v39, v108, v38
	v_add_f32_e32 v19, v116, v19
	v_mul_f32_e32 v39, 0x3fb8aa3b, v39
	v_add_f32_e32 v19, v117, v19
	v_exp_f32_e32 v125, v39
	v_sub_f32_e32 v39, v111, v38
	v_add_f32_e32 v19, v118, v19
	v_mul_f32_e32 v39, 0x3fb8aa3b, v39
	v_add_f32_e32 v19, v119, v19
	v_exp_f32_e32 v126, v39
	v_sub_f32_e32 v39, v110, v38
	v_add_f32_e32 v19, v67, v19
	v_mul_f32_e32 v39, 0x3fb8aa3b, v39
	v_add_f32_e32 v19, v66, v19
	v_exp_f32_e32 v127, v39
	v_sub_f32_e32 v39, v113, v38
	v_add_f32_e32 v19, v120, v19
	v_mul_f32_e32 v39, 0x3fb8aa3b, v39
	v_add_f32_e32 v19, v121, v19
	v_exp_f32_e32 v128, v39
	v_sub_f32_e32 v39, v112, v38
	v_add_f32_e32 v19, v122, v19
	v_mul_f32_e32 v39, 0x3fb8aa3b, v39
	v_add_f32_e32 v19, v123, v19
	v_exp_f32_e32 v129, v39
	v_sub_f32_e32 v39, v115, v38
	v_add_f32_e32 v19, v124, v19
	v_mul_f32_e32 v39, 0x3fb8aa3b, v39
	v_add_f32_e32 v19, v125, v19
	v_exp_f32_e32 v130, v39
	v_sub_f32_e32 v39, v114, v38
	v_add_f32_e32 v19, v126, v19
	v_mul_f32_e32 v39, 0x3fb8aa3b, v39
	v_sub_f32_e32 v25, v25, v38
	v_add_f32_e32 v19, v127, v19
	v_exp_f32_e32 v131, v39
	v_mul_f32_e32 v25, 0x3fb8aa3b, v25
	v_sub_f32_e32 v24, v24, v38
	v_add_f32_e32 v19, v128, v19
	v_exp_f32_e32 v132, v25
	v_mul_f32_e32 v24, 0x3fb8aa3b, v24
	v_sub_f32_e32 v21, v21, v38
	v_add_f32_e32 v19, v129, v19
	v_exp_f32_e32 v133, v24
	v_mul_f32_e32 v21, 0x3fb8aa3b, v21
	v_sub_f32_e32 v20, v20, v38
	v_add_f32_e32 v19, v130, v19
	v_exp_f32_e32 v134, v21
	v_mul_f32_e32 v20, 0x3fb8aa3b, v20
	v_sub_f32_e32 v17, v17, v38
	v_add_f32_e32 v19, v131, v19
	v_exp_f32_e32 v135, v20
	v_mul_f32_e32 v17, 0x3fb8aa3b, v17
	v_sub_f32_e32 v16, v16, v38
	v_add_f32_e32 v19, v132, v19
	v_exp_f32_e32 v136, v17
	v_mul_f32_e32 v16, 0x3fb8aa3b, v16
	v_add_f32_e32 v19, v133, v19
	v_exp_f32_e32 v137, v16
	v_add_f32_e32 v19, v134, v19
	v_add_f32_e32 v19, v135, v19
	v_add_f32_e32 v17, v136, v19
	v_add_f32_e32 v16, v137, v17
	v_mov_b32_e32 v17, v16
	s_nop 1
	v_permlane16_swap_b32_e32 v17, v16
	v_add_u32_e32 v24, v74, v28
	v_cvt_pk_bf16_f32 v19, v55, v59
	v_add_u32_e32 v28, v24, v75
	v_add_u32_e32 v55, v24, v76
	s_waitcnt lgkmcnt(0)
	v_add_f32_e32 v39, v16, v17
	v_cvt_pk_bf16_f32 v16, v18, v22
	v_cvt_pk_bf16_f32 v17, v23, v26
	v_cvt_pk_bf16_f32 v18, v27, v56
	ds_read2st64_b64 v[20:23], v28 offset1:4
	ds_read2st64_b64 v[24:27], v55 offset1:4
	v_mov_b32_e32 v54, v39
	s_nop 1
	v_permlane32_swap_b32_e32 v54, v39
	s_waitcnt lgkmcnt(1)
	v_mov_b32_e32 v58, v20
	s_waitcnt lgkmcnt(0)
	v_mov_b32_e32 v60, v24
	v_mov_b32_e32 v61, v25
	v_mov_b32_e32 v24, v22
	v_mov_b32_e32 v25, v23
	v_mov_b32_e32 v59, v21
	v_add_f32_e32 v54, v39, v54
	v_mfma_f32_16x16x32_bf16 v[20:23], v[24:27], v[16:19], 0
	ds_read2st64_b64 v[24:27], v28 offset0:8 offset1:12
	ds_read2st64_b64 v[62:65], v55 offset0:8 offset1:12
	v_add_u32_e32 v28, v74, v29
	v_add_u32_e32 v29, v28, v75
	v_add_u32_e32 v28, v28, v76
	s_waitcnt lgkmcnt(1)
; #define LAS __attribute__((address_space(3)))
; DI unsigned pk2(float lo, float hi) { f32x2 v = {lo, hi}; bf16v2 b = __builtin_convertvector(v, bf16v2); return __builtin_bit_cast(unsigned, b); }
; #define MFMA32(a, b, c) __builtin_amdgcn_mfma_f32_16x16x32_bf16((a), (b), (c), 0, 0, 0)
; DI void na_phase(LAS unsigned char* lds, const Args& A, const bf16* proj, bf16* nao, int T, int nB, unsigned* counter, int tid_in) {
;     ...
; #pragma unroll
;             for (int rr = 0; rr < 4; ++rr) { const int sl = (rs + 4 * kh + rr) & 7;
;                 const u32x4 pw = (u32x4){pk2(sT[rr][0][0], sT[rr][0][1]), pk2(sT[rr][0][2], sT[rr][0][3]), pk2(sT[rr][1][0], sT[rr][1][1]), pk2(sT[rr][1][2], sT[rr][1][3])};
;                 const bf16x8 pb = __builtin_bit_cast(bf16x8, pw);
; #pragma unroll
;                 for (int mt = 0; mt < 4; ++mt) { const int dd = 16 * mt + l15, sw = 2 * ((dd >> 1) & 7);
;                     const LAS unsigned char* vb = lds + NA_V + sl * 8192 + dd * 128;
;                     const u32x2 lo = *(const LAS u32x2*)(vb + ((((cs0 >> 2) + g) ^ sw) * 8)), hi = *(const LAS u32x2*)(vb + ((((cs0 >> 2) + 4 + g) ^ sw) * 8));
;                     const u32x4 vv = (u32x4){lo.x, lo.y, hi.x, hi.y};
;                     O[mt] = MFMA32(__builtin_bit_cast(bf16x8, vv), pb, O[mt]); } }
;             LAS float* MG = (LAS float*)(lds + NA_MRG + qg * 4608) + lane;
;             if (kh == 1) { MG[0] = mx; MG[64] = lsum;
; #pragma unroll
;                 for (int mt = 0; mt < 4; ++mt)
; #pragma unroll
;                     for (int e = 0; e < 4; ++e) MG[(2 + mt * 4 + e) * 64] = O[mt][e]; }
	v_mov_b32_e32 v104, v24
	v_mov_b32_e32 v105, v25
	s_waitcnt lgkmcnt(0)
	v_mov_b32_e32 v106, v62
	v_mov_b32_e32 v107, v63
	v_mov_b32_e32 v62, v26
	v_mov_b32_e32 v63, v27
	v_mfma_f32_16x16x32_bf16 v[58:61], v[58:61], v[16:19], 0
	ds_read2st64_b64 v[108:111], v28 offset1:4
	v_cvt_pk_bf16_f32 v24, v116, v117
	v_cvt_pk_bf16_f32 v25, v118, v119
	v_mfma_f32_16x16x32_bf16 v[104:107], v[104:107], v[16:19], 0
	v_cvt_pk_bf16_f32 v26, v67, v66
	s_waitcnt lgkmcnt(0)
	v_mov_b32_e32 v114, v108
	v_mov_b32_e32 v115, v109
	v_mfma_f32_16x16x32_bf16 v[16:19], v[62:65], v[16:19], 0
	ds_read2st64_b64 v[62:65], v29 offset1:4
	v_cvt_pk_bf16_f32 v27, v120, v121
	s_waitcnt lgkmcnt(0)
	v_mov_b32_e32 v108, v64
	v_mov_b32_e32 v109, v65
	v_mov_b32_e32 v112, v62
	v_mov_b32_e32 v113, v63
	v_mfma_f32_16x16x32_bf16 v[20:23], v[108:111], v[24:27], v[20:23]
	ds_read2st64_b64 v[62:65], v29 offset0:8 offset1:12
	ds_read2st64_b64 v[108:111], v28 offset0:8 offset1:12
	v_add_u32_e32 v28, v74, v30
	v_add_u32_e32 v29, v28, v75
	v_mfma_f32_16x16x32_bf16 v[58:61], v[112:115], v[24:27], v[58:61]
	v_add_u32_e32 v28, v28, v76
	s_waitcnt lgkmcnt(0)
	v_mov_b32_e32 v114, v108
	v_mov_b32_e32 v115, v109
	v_mov_b32_e32 v108, v64
	v_mov_b32_e32 v109, v65
	v_mov_b32_e32 v112, v62
	v_mov_b32_e32 v113, v63
	v_mfma_f32_16x16x32_bf16 v[16:19], v[108:111], v[24:27], v[16:19]
	ds_read2st64_b64 v[62:65], v29 offset1:4
	ds_read2st64_b64 v[108:111], v28 offset1:4
	v_mfma_f32_16x16x32_bf16 v[104:107], v[112:115], v[24:27], v[104:107]
	v_cvt_pk_bf16_f32 v24, v122, v123
	v_cvt_pk_bf16_f32 v25, v124, v125
	s_waitcnt lgkmcnt(0)
	v_mov_b32_e32 v114, v108
	v_mov_b32_e32 v115, v109
	v_mov_b32_e32 v108, v64
	v_mov_b32_e32 v109, v65
	v_cvt_pk_bf16_f32 v26, v126, v127
	v_cvt_pk_bf16_f32 v27, v128, v129
	v_mov_b32_e32 v112, v62
	v_mov_b32_e32 v113, v63
	v_mfma_f32_16x16x32_bf16 v[20:23], v[108:111], v[24:27], v[20:23]
	ds_read2st64_b64 v[62:65], v29 offset0:8 offset1:12
	ds_read2st64_b64 v[108:111], v28 offset0:8 offset1:12
	v_add_u32_e32 v28, v74, v31
	v_add_u32_e32 v55, v28, v75
	v_mfma_f32_16x16x32_bf16 v[58:61], v[112:115], v[24:27], v[58:61]
	s_waitcnt lgkmcnt(1)
	v_mov_b32_e32 v112, v62
	v_mov_b32_e32 v113, v63
	s_waitcnt lgkmcnt(0)
	v_mov_b32_e32 v114, v108
	v_mov_b32_e32 v115, v109
	v_mov_b32_e32 v108, v64
	v_mov_b32_e32 v109, v65
	v_add_u32_e32 v56, v28, v76
	v_mfma_f32_16x16x32_bf16 v[104:107], v[112:115], v[24:27], v[104:107]
	v_cvt_pk_bf16_f32 v62, v130, v131
	v_cvt_pk_bf16_f32 v63, v132, v133
	v_cvt_pk_bf16_f32 v64, v134, v135
	v_mfma_f32_16x16x32_bf16 v[16:19], v[108:111], v[24:27], v[16:19]
	ds_read2st64_b64 v[24:27], v55 offset1:4
	ds_read2st64_b64 v[108:111], v56 offset1:4
	v_cvt_pk_bf16_f32 v65, v136, v137
	s_waitcnt lgkmcnt(1)
	v_mov_b32_e32 v28, v24
	v_mov_b32_e32 v29, v25
	s_waitcnt lgkmcnt(0)
	v_mov_b32_e32 v30, v108
	v_mov_b32_e32 v31, v109
	v_mov_b32_e32 v108, v26
	v_mov_b32_e32 v109, v27
	v_mfma_f32_16x16x32_bf16 v[28:31], v[28:31], v[62:65], v[58:61]
	s_nop 0
	v_mfma_f32_16x16x32_bf16 v[24:27], v[108:111], v[62:65], v[20:23]
	s_nop 0
	ds_read2st64_b64 v[58:61], v55 offset0:8 offset1:12
	ds_read2st64_b64 v[108:111], v56 offset0:8 offset1:12
	s_waitcnt lgkmcnt(1)
	v_mov_b32_e32 v20, v58
	v_mov_b32_e32 v21, v59
	s_waitcnt lgkmcnt(0)
	v_mov_b32_e32 v22, v108
	v_mov_b32_e32 v23, v109
	v_mov_b32_e32 v108, v60
	v_mov_b32_e32 v109, v61
	v_mfma_f32_16x16x32_bf16 v[20:23], v[20:23], v[62:65], v[104:107]
	s_nop 0
	v_mfma_f32_16x16x32_bf16 v[16:19], v[108:111], v[62:65], v[16:19]
	s_and_saveexec_b64 s[0:1], s[42:43]
	s_cbranch_execz .LBB0_403
	ds_write2st64_b32 v103, v38, v54 offset1:1
	ds_write2st64_b32 v103, v28, v29 offset0:2 offset1:3
	ds_write2st64_b32 v103, v30, v31 offset0:4 offset1:5
	ds_write2st64_b32 v103, v24, v25 offset0:6 offset1:7
	ds_write2st64_b32 v103, v26, v27 offset0:8 offset1:9
	ds_write2st64_b32 v103, v20, v21 offset0:10 offset1:11
	ds_write2st64_b32 v103, v22, v23 offset0:12 offset1:13
	ds_write2st64_b32 v103, v16, v17 offset0:14 offset1:15
	ds_write2st64_b32 v103, v18, v19 offset0:16 offset1:17
